# MoBA softmax: 28 scale-and-shift fmas per step issued as 14 packed v_pk_fma_f32 in the computing-wave path
# baseline (speedup 1.0000x reference)
.Lms_inter:
	v_mov_b32_e32 v198, v197
	s_nop 1
	v_permlane16_swap_b32_e32 v197, v198
	v_max_f32_e32 v197, v197, v198
	v_mov_b32_e32 v198, v197
	s_nop 1
	v_permlane32_swap_b32_e32 v197, v198
	v_max3_f32 v197, v196, v197, v198
	v_cmp_neq_f32_e32 vcc, s73, v197
	s_nop 1
	v_cndmask_b32_e32 v198, 0, v197, vcc
	v_sub_f32_e32 v196, v196, v198
	v_mul_f32_e32 v199, 0x3e0293ee, v196
	v_mul_f32_e32 v196, 0xbe0293ee, v198
	v_cndmask_b32_e64 v198, v196, v215, s[0:1]
	s_mov_b32 s86, 0x3e0293ee
	v_pk_fma_f32 v[112:113], v[112:113], s[86:87], v[198:199] op_sel_hi:[1,0,0]
	v_pk_fma_f32 v[114:115], v[114:115], s[86:87], v[198:199] op_sel_hi:[1,0,0]
	s_xor_b32 s87, s15, 1
	v_pk_fma_f32 v[108:109], v[108:109], s[86:87], v[198:199] op_sel_hi:[1,0,0]
	s_mul_i32 s87, s87, 0x11000
	v_exp_f32_e32 v112, v112
	s_add_i32 s87, s87, 0
	v_exp_f32_e32 v113, v113
	v_pk_fma_f32 v[110:111], v[110:111], s[86:87], v[198:199] op_sel_hi:[1,0,0]
	v_add3_u32 v224, s87, v165, v216
	v_exp_f32_e32 v114, v114
	v_add3_u32 v223, s87, v0, v216
	v_exp_f32_e32 v115, v115
	v_add_u32_e32 v225, 0x8800, v224
	v_pk_fma_f32 v[104:105], v[104:105], s[86:87], v[198:199] op_sel_hi:[1,0,0]
	v_exp_f32_e32 v108, v108
	s_waitcnt vmcnt(7)
	v_add_f32_e32 v196, 0, v112
	ds_write_b128 v223, v[4:7]
	v_exp_f32_e32 v109, v109
	s_waitcnt vmcnt(6)
	v_add_f32_e32 v196, v113, v196
	v_pk_fma_f32 v[106:107], v[106:107], s[86:87], v[198:199] op_sel_hi:[1,0,0]
	ds_write2_b64 v225, v[8:9], v[10:11] offset1:2
	v_exp_f32_e32 v110, v110
	s_waitcnt vmcnt(5)
	v_add_f32_e32 v196, v114, v196
	ds_write_b128 v223, v[12:15] offset:8704
	v_exp_f32_e32 v111, v111
	v_add_f32_e32 v196, v115, v196
	v_add_u32_e32 v225, 0xa800, v224
	v_pk_fma_f32 v[100:101], v[100:101], s[86:87], v[198:199] op_sel_hi:[1,0,0]
	s_waitcnt vmcnt(4)
	v_exp_f32_e32 v104, v104
	ds_write2_b64 v225, v[16:17], v[18:19] offset0:64 offset1:66
	v_add_f32_e32 v196, v108, v196
	v_exp_f32_e32 v105, v105
	s_waitcnt vmcnt(3)
	v_add_f32_e32 v196, v109, v196
	ds_write_b128 v223, v[20:23] offset:17408
	v_pk_fma_f32 v[102:103], v[102:103], s[86:87], v[198:199] op_sel_hi:[1,0,0]
	v_add_u32_e32 v225, 0xc800, v224
	v_exp_f32_e32 v106, v106
	v_add_f32_e32 v196, v110, v196
	s_waitcnt vmcnt(2)
	v_exp_f32_e32 v107, v107
	ds_write2_b64 v225, v[24:25], v[26:27] offset0:128 offset1:130
	v_add_f32_e32 v196, v111, v196
	s_waitcnt vmcnt(1)
	v_pk_fma_f32 v[96:97], v[96:97], s[86:87], v[198:199] op_sel_hi:[1,0,0]
	v_exp_f32_e32 v100, v100
	ds_write_b128 v223, v[28:31] offset:26112
	v_add_f32_e32 v196, v104, v196
	v_add_u32_e32 v223, 0xe800, v224
	v_exp_f32_e32 v101, v101
	s_waitcnt vmcnt(0)
	v_add_f32_e32 v196, v105, v196
	ds_write2_b64 v223, v[32:33], v[34:35] offset0:192 offset1:194
	s_andn2_b64 vcc, exec, s[80:81]
	s_cbranch_vccnz .Lms_t2plain
	v_pk_fma_f32 v[98:99], v[98:99], s[86:87], v[198:199] op_sel_hi:[1,0,0]
	v_exp_f32_e32 v102, v102
	s_lshr_b32 s82, s14, 1
	v_add_f32_e32 v196, v106, v196
	v_exp_f32_e32 v103, v103
	s_sub_i32 s82, s47, s82
	v_add_f32_e32 v196, v107, v196
	s_lshl_b32 s83, s14, 7
	v_pk_fma_f32 v[92:93], v[92:93], s[86:87], v[198:199] op_sel_hi:[1,0,0]
	v_exp_f32_e32 v96, v96
	s_lshl_b32 s82, s82, 8
	v_add_f32_e32 v196, v100, v196
	v_exp_f32_e32 v97, v97
	s_and_b32 s83, s83, 0x80
	v_add_f32_e32 v196, v101, v196
	s_or_b32 s82, s82, s83
	v_pk_fma_f32 v[94:95], v[94:95], s[86:87], v[198:199] op_sel_hi:[1,0,0]
	v_exp_f32_e32 v98, v98
	s_ashr_i32 s83, s82, 31
	v_add_f32_e32 v196, v102, v196
	v_exp_f32_e32 v99, v99
	v_lshl_add_u64 v[28:29], s[82:83], 1, v[118:119]
	v_add_f32_e32 v196, v103, v196
	s_mul_i32 s82, s82, s72
	v_pk_fma_f32 v[88:89], v[88:89], s[86:87], v[198:199] op_sel_hi:[1,0,0]
	v_exp_f32_e32 v92, v92
	s_add_u32 s82, s82, s3
	v_add_f32_e32 v196, v96, v196
	s_mov_b32 s83, 0
	v_exp_f32_e32 v93, v93
	v_add_f32_e32 v196, v97, v196
	v_lshl_add_u64 v[4:5], v[250:251], 0, s[82:83]
	v_pk_fma_f32 v[90:91], v[90:91], s[86:87], v[198:199] op_sel_hi:[1,0,0]
	v_exp_f32_e32 v94, v94
	v_lshl_add_u64 v[8:9], v[28:29], 0, v[146:147]
	v_add_f32_e32 v196, v98, v196
	s_add_u32 s82, s82, 0x3c000
	v_exp_f32_e32 v95, v95
	v_add_f32_e32 v196, v99, v196
	v_lshl_add_u64 v[12:13], v[250:251], 0, s[82:83]
	v_exp_f32_e32 v88, v88
	v_add_f32_e32 v196, v92, v196
	v_lshl_add_u64 v[16:17], v[28:29], 0, v[148:149]
	v_exp_f32_e32 v89, v89
	s_add_u32 s82, s82, 0x3c000
	v_add_f32_e32 v196, v93, v196
	v_exp_f32_e32 v90, v90
	v_lshl_add_u64 v[20:21], v[250:251], 0, s[82:83]
	v_add_f32_e32 v196, v94, v196
	v_exp_f32_e32 v91, v91
	v_lshl_add_u64 v[24:25], v[28:29], 0, v[150:151]
	v_add_f32_e32 v196, v95, v196
	s_add_u32 s82, s82, 0x3c000
	v_add_f32_e32 v196, v88, v196
	v_add_f32_e32 v196, v89, v196
	v_lshl_add_u64 v[30:31], v[250:251], 0, s[82:83]
	v_add_f32_e32 v196, v90, v196
	v_lshl_add_u64 v[32:33], v[28:29], 0, v[152:153]
	v_fmamk_f32 v84, v84, 0x3e0293ee, v198
	v_add_f32_e32 v200, v91, v196
	global_load_dwordx4 v[4:7], v[4:5], off offset:1024
	v_exp_f32_e32 v196, v84
	v_fmamk_f32 v85, v85, 0x3e0293ee, v198
	global_load_dwordx4 v[8:11], v[8:9], off
	v_exp_f32_e32 v85, v85
	global_load_dwordx4 v[12:15], v[12:13], off offset:1024
	v_fmamk_f32 v86, v86, 0x3e0293ee, v198
	v_exp_f32_e32 v86, v86
	global_load_dwordx4 v[16:19], v[16:17], off
	v_fmac_f32_e32 v198, 0x3e0293ee, v87
	v_exp_f32_e32 v87, v198
	global_load_dwordx4 v[20:23], v[20:21], off offset:1024
	v_add_f32_e32 v84, v196, v200
	global_load_dwordx4 v[24:27], v[24:25], off
	v_add_f32_e32 v84, v85, v84
	v_add_f32_e32 v84, v86, v84
	global_load_dwordx4 v[28:31], v[30:31], off offset:1024
	v_add_f32_e32 v198, v87, v84
	global_load_dwordx4 v[32:35], v[32:33], off
	s_branch .Lms_join
.Lms_t2plain:
	v_pk_fma_f32 v[98:99], v[98:99], s[86:87], v[198:199] op_sel_hi:[1,0,0]
	v_exp_f32_e32 v102, v102
	v_add_f32_e32 v196, v106, v196
	v_exp_f32_e32 v103, v103
	v_add_f32_e32 v196, v107, v196
	v_pk_fma_f32 v[92:93], v[92:93], s[86:87], v[198:199] op_sel_hi:[1,0,0]
	v_exp_f32_e32 v96, v96
	v_add_f32_e32 v196, v100, v196
	v_exp_f32_e32 v97, v97
	v_add_f32_e32 v196, v101, v196
	v_pk_fma_f32 v[94:95], v[94:95], s[86:87], v[198:199] op_sel_hi:[1,0,0]
	v_exp_f32_e32 v98, v98
	v_add_f32_e32 v196, v102, v196
	v_exp_f32_e32 v99, v99
	v_add_f32_e32 v196, v103, v196
	v_pk_fma_f32 v[88:89], v[88:89], s[86:87], v[198:199] op_sel_hi:[1,0,0]
	v_exp_f32_e32 v92, v92
	v_add_f32_e32 v196, v96, v196
	v_exp_f32_e32 v93, v93
	v_add_f32_e32 v196, v97, v196
	v_pk_fma_f32 v[90:91], v[90:91], s[86:87], v[198:199] op_sel_hi:[1,0,0]
	v_exp_f32_e32 v94, v94
	v_add_f32_e32 v196, v98, v196
	v_exp_f32_e32 v95, v95
	v_add_f32_e32 v196, v99, v196
	v_exp_f32_e32 v88, v88
	v_add_f32_e32 v196, v92, v196
	v_exp_f32_e32 v89, v89
	v_add_f32_e32 v196, v93, v196
	v_exp_f32_e32 v90, v90
	v_add_f32_e32 v196, v94, v196
	v_exp_f32_e32 v91, v91
	v_add_f32_e32 v196, v95, v196
	v_add_f32_e32 v196, v88, v196
	v_add_f32_e32 v196, v89, v196
	v_add_f32_e32 v196, v90, v196
	v_fmamk_f32 v84, v84, 0x3e0293ee, v198
	v_add_f32_e32 v200, v91, v196
	v_exp_f32_e32 v196, v84
	v_fmamk_f32 v85, v85, 0x3e0293ee, v198
	v_exp_f32_e32 v85, v85
	v_fmamk_f32 v86, v86, 0x3e0293ee, v198
	v_exp_f32_e32 v86, v86
	v_fmac_f32_e32 v198, 0x3e0293ee, v87
	v_exp_f32_e32 v87, v198
	v_add_f32_e32 v84, v196, v200
	v_add_f32_e32 v84, v85, v84
	v_add_f32_e32 v84, v86, v84
	v_add_f32_e32 v198, v87, v84
